# P4 V^T copy (on top of the G==256 unrolled path): transposed tile restaged through a second LDS image so each store instruction writes 8 full 128-B lines instead of 64 strided 16-B pieces
# baseline (speedup 1.0000x reference)
; #define LAS __attribute__((address_space(3)))
; __global__ void __launch_bounds__(512, 2) fwd_mega(Args args) {
;     ...
;             { LAS bf16* T = (LAS bf16*)lds; const int r = tid >> 3, j = tid & 7, dd = tid & 127, kq = tid >> 7;
;               int idx = bx; u32x4 ta = {0u, 0u, 0u, 0u}, tb = {0u, 0u, 0u, 0u};
;               if (idx < 2048) { const int rem = idx & 1023, b_ = rem >> 8, hq = (rem >> 5) & 7, st = rem & 31; const bf16* p = PROJ + (size_t)(b_ * SEQ + 64 * st + r) * PROJW + ((idx >> 10) ? 4096 : 2048) + 128 * hq + 8 * j;
;                   ta = *(const u32x4*)p; tb = *(const u32x4*)(p + 64); }
;               for (; idx < 2048; idx += G) {
;                   *(LAS u32x4*)(T + r * QP + 8 * j) = ta; *(LAS u32x4*)(T + r * QP + 64 + 8 * j) = tb;
;                   __syncthreads();
;                   if (idx + G < 2048) { const int i2 = idx + G, rem = i2 & 1023, b_ = rem >> 8, hq = (rem >> 5) & 7, st = rem & 31; const bf16* p = PROJ + (size_t)(b_ * SEQ + 64 * st + r) * PROJW + ((i2 >> 10) ? 4096 : 2048) + 128 * hq + 8 * j;
;                       ta = *(const u32x4*)p; tb = *(const u32x4*)(p + 64); }
;                   unsigned v[16];
; #pragma unroll
;                   for (int i = 0; i < 16; ++i) { const int key = (idx >> 10) ? (16 * kq + i) : (32 * (kq >> 1) + 16 * ((i >> 2) & 1) + 8 * (kq & 1) + 4 * (i >> 3) + (i & 3)); v[i] = T[key * QP + dd]; }
;                   u32x4 o0, o1; o0.x = v[0] | (v[1] << 16); o0.y = v[2] | (v[3] << 16); o0.z = v[4] | (v[5] << 16); o0.w = v[6] | (v[7] << 16);
;                   o1.x = v[8] | (v[9] << 16); o1.y = v[10] | (v[11] << 16); o1.z = v[12] | (v[13] << 16); o1.w = v[14] | (v[15] << 16);
;                   { const int rem = idx & 1023, b_ = rem >> 8, hq = (rem >> 5) & 7, st = rem & 31;
;                     bf16* dst = ((idx >> 10) ? VTG : VTA) + ((size_t)(b_ * 8 + hq) * 128 + dd) * SEQ + 64 * st + 16 * kq;
;                     *(u32x4*)dst = o0; *(u32x4*)(dst + 8) = o1; }
;                   __syncthreads();
.Lvt8:
	v_lshrrev_b32_e32 v150, 3, v238
	v_lshlrev_b32_e32 v150, 11, v150
	v_and_b32_e32 v156, 7, v238
	v_lshlrev_b32_e32 v156, 3, v156
	v_mov_b32_e32 v157, 0
	v_and_b32_e32 v151, 0x7f, v238
	v_mul_u32_u24_e32 v151, 0x90, v151
	v_lshrrev_b32_e32 v158, 7, v238
	v_lshl_add_u32 v151, v158, 5, v151
	v_add_u32_e32 v151, 0x5000, v151
	v_lshrrev_b32_e32 v158, 3, v238
	v_mul_u32_u24_e32 v158, 0x90, v158
	v_and_b32_e32 v159, 7, v238
	v_lshl_add_u32 v158, v159, 4, v158
	v_add_u32_e32 v158, 0x5000, v158
	v_ashrrev_i32_e32 v9, 3, v238
	v_readlane_b32 s0, v253, 14
	v_mov_b64_e32 v[0:1], s[38:39]
	v_and_b32_e32 v8, 7, v238
	v_add_u32_e32 v2, s0, v9
	v_mad_i64_i32 v[0:1], s[10:11], v2, s97, v[0:1]
	v_readlane_b32 s10, v255, 21
	s_mov_b32 s0, s10
	v_readlane_b32 s11, v255, 22
	v_writelane_b32 v255, s0, 21
	s_mov_b32 s11, s27
	v_lshl_add_u64 v[0:1], v[0:1], 0, s[10:11]
	v_writelane_b32 v255, s1, 22
	v_lshlrev_b32_e32 v152, 4, v8
	v_readlane_b32 s10, v255, 23
	v_readlane_b32 s11, v255, 24
	s_mov_b32 s11, s27
	v_ashrrev_i32_e32 v11, 7, v238
	v_lshl_add_u64 v[0:1], v[0:1], 0, s[10:11]
	v_lshl_add_u64 v[134:135], v[0:1], 0, v[152:153]
	s_mov_b64 s[24:25], 0x1800000
	s_mov_b64 s[36:37], 0x1000
	v_lshl_add_u64 v[136:137], v[134:135], 0, s[24:25]
	v_lshl_add_u64 v[138:139], v[136:137], 0, s[24:25]
	v_lshl_add_u64 v[140:141], v[138:139], 0, s[24:25]
	v_lshl_add_u64 v[142:143], v[134:135], 0, s[36:37]
	v_lshl_add_u64 v[144:145], v[136:137], 0, s[36:37]
	v_lshl_add_u64 v[146:147], v[138:139], 0, s[36:37]
	v_lshl_add_u64 v[148:149], v[140:141], 0, s[36:37]
	global_load_dwordx4 v[60:63], v[134:135], off
	global_load_dwordx4 v[64:67], v[134:135], off offset:128
	global_load_dwordx4 v[68:71], v[136:137], off
	global_load_dwordx4 v[72:75], v[136:137], off offset:128
	global_load_dwordx4 v[76:79], v[138:139], off
	global_load_dwordx4 v[80:83], v[138:139], off offset:128
	global_load_dwordx4 v[84:87], v[140:141], off
	global_load_dwordx4 v[88:91], v[140:141], off offset:128
	global_load_dwordx4 v[92:95], v[142:143], off
	global_load_dwordx4 v[96:99], v[142:143], off offset:128
	global_load_dwordx4 v[108:111], v[144:145], off
	global_load_dwordx4 v[112:115], v[144:145], off offset:128
	global_load_dwordx4 v[116:119], v[146:147], off
	global_load_dwordx4 v[120:123], v[146:147], off offset:128
	global_load_dwordx4 v[126:129], v[148:149], off
	global_load_dwordx4 v[130:133], v[148:149], off offset:128
	s_mov_b32 s0, s10
	v_lshlrev_b32_e32 v10, 4, v11
	v_and_b32_e32 v15, 0xffffffe0, v9
	v_lshlrev_b32_e32 v11, 3, v11
	v_writelane_b32 v255, s0, 23
	v_and_b32_e32 v13, 0x7f, v238
	v_lshlrev_b32_e32 v12, 3, v8
	v_mul_lo_u32 v8, v9, s94
	v_and_or_b32 v15, v11, 8, v15
	v_writelane_b32 v255, s1, 24
	v_add3_u32 v14, 0, v8, v152
	v_lshl_add_u32 v8, v13, 1, 0
	v_lshlrev_b32_e32 v16, 11, v13
	v_ashrrev_i32_e32 v11, 31, v10
	v_or_b32_e32 v17, 4, v10
	v_or_b32_e32 v18, 16, v15
	v_or_b32_e32 v19, 5, v10
	v_or_b32_e32 v20, 17, v15
	v_or_b32_e32 v21, 6, v10
	v_or_b32_e32 v22, 18, v15
	v_or_b32_e32 v23, 7, v10
	v_or_b32_e32 v24, 19, v15
	v_or_b32_e32 v25, 8, v10
	v_or_b32_e32 v26, 4, v15
	v_or_b32_e32 v27, 9, v10
	v_or_b32_e32 v28, 5, v15
	v_or_b32_e32 v29, 10, v10
	v_or_b32_e32 v30, 6, v15
	v_or_b32_e32 v31, 11, v10
	v_or_b32_e32 v32, 7, v15
	v_or_b32_e32 v33, 12, v10
	v_or_b32_e32 v34, 20, v15
	v_or_b32_e32 v35, 13, v10
	v_or_b32_e32 v36, 21, v15
	v_or_b32_e32 v37, 14, v10
	v_or_b32_e32 v38, 22, v15
	v_or_b32_e32 v39, 15, v10
	v_or_b32_e32 v40, 23, v15
	v_lshlrev_b32_e32 v12, 1, v12
	v_readlane_b32 s0, v254, 59
	v_readlane_b32 s14, v254, 54
	v_readlane_b32 s16, v253, 13
	v_readlane_b32 s15, v254, 53
	s_mov_b32 s23, s2
	s_add_i32 s17, s23, s52
	s_cmpk_gt_i32 s17, 0x7ff
	s_cselect_b64 s[10:11], -1, 0
	s_waitcnt vmcnt(14)
	ds_write_b128 v14, v[60:63]
	ds_write_b128 v14, v[64:67] offset:128
	s_waitcnt lgkmcnt(0)
	s_barrier
	v_readlane_b32 s22, v254, 57
	s_add_i32 s22, s16, s22
	s_cmpk_lt_u32 s23, 0x400
	s_cselect_b64 vcc, -1, 0
	v_cndmask_b32_e32 v13, v10, v15, vcc
	v_mad_u64_u32 v[42:43], s[24:25], v13, s94, v[8:9]
	ds_read_u16 v13, v42
	ds_read_u16 v41, v42 offset:288
	ds_read_u16 v44, v42 offset:576
	ds_read_u16 v45, v42 offset:864
	v_cndmask_b32_e32 v42, v17, v18, vcc
	v_mad_u64_u32 v[42:43], s[24:25], v42, s94, v[8:9]
	ds_read_u16 v46, v42
	v_cndmask_b32_e32 v42, v19, v20, vcc
	v_mad_u64_u32 v[42:43], s[24:25], v42, s94, v[8:9]
	ds_read_u16 v47, v42
	v_cndmask_b32_e32 v42, v21, v22, vcc
	v_mad_u64_u32 v[42:43], s[24:25], v42, s94, v[8:9]
	ds_read_u16 v48, v42
	v_cndmask_b32_e32 v42, v23, v24, vcc
	v_mad_u64_u32 v[42:43], s[24:25], v42, s94, v[8:9]
	ds_read_u16 v49, v42
	v_cndmask_b32_e32 v42, v25, v26, vcc
	v_mad_u64_u32 v[42:43], s[24:25], v42, s94, v[8:9]
	ds_read_u16 v50, v42
	v_cndmask_b32_e32 v42, v27, v28, vcc
	v_mad_u64_u32 v[42:43], s[24:25], v42, s94, v[8:9]
	ds_read_u16 v51, v42
	v_cndmask_b32_e32 v42, v29, v30, vcc
	v_mad_u64_u32 v[42:43], s[24:25], v42, s94, v[8:9]
	ds_read_u16 v52, v42
	v_cndmask_b32_e32 v42, v31, v32, vcc
	v_mad_u64_u32 v[42:43], s[24:25], v42, s94, v[8:9]
	ds_read_u16 v53, v42
	v_cndmask_b32_e32 v42, v33, v34, vcc
	v_mad_u64_u32 v[42:43], s[24:25], v42, s94, v[8:9]
	ds_read_u16 v54, v42
	v_cndmask_b32_e32 v42, v35, v36, vcc
	v_mad_u64_u32 v[42:43], s[24:25], v42, s94, v[8:9]
	ds_read_u16 v55, v42
	v_cndmask_b32_e32 v42, v37, v38, vcc
	v_mad_u64_u32 v[42:43], s[24:25], v42, s94, v[8:9]
	ds_read_u16 v56, v42
	s_and_b64 s[24:25], vcc, exec
	v_cndmask_b32_e32 v42, v39, v40, vcc
	s_cselect_b32 s25, s29, s80
	s_cselect_b32 s24, s28, s71
	v_mad_u64_u32 v[42:43], s[36:37], v42, s94, v[8:9]
	s_and_b32 s23, s0, 0x7c0000
	ds_read_u16 v57, v42
	s_waitcnt lgkmcnt(14)
	v_lshl_or_b32 v42, v41, 16, v13
	v_or_b32_e32 v13, s23, v150
	v_lshlrev_b32_e32 v152, 1, v13
	s_and_b32 s16, s16, 0x7c0
	s_waitcnt lgkmcnt(12)
	v_lshl_or_b32 v43, v45, 16, v44
	s_waitcnt lgkmcnt(10)
	v_lshl_or_b32 v44, v47, 16, v46
	s_waitcnt lgkmcnt(6)
	v_lshl_or_b32 v46, v51, 16, v50
	v_lshl_add_u64 v[50:51], s[24:25], 0, v[152:153]
	s_lshl_b32 s26, s16, 1
	v_readlane_b32 s16, v254, 58
	v_lshl_add_u64 v[50:51], v[50:51], 0, s[26:27]
	s_add_i32 s14, s14, s16
	v_readlane_b32 s16, v254, 60
	v_lshl_or_b32 v45, v49, 16, v48
	v_lshl_add_u64 v[50:51], v[156:157], 1, v[50:51]
	s_add_i32 s15, s15, s33
	s_add_i32 s0, s0, s16
	s_and_b64 vcc, exec, s[10:11]
	s_mov_b32 s16, s22
	s_mov_b32 s23, s17
	s_waitcnt lgkmcnt(4)
	v_lshl_or_b32 v47, v53, 16, v52
	s_waitcnt lgkmcnt(2)
	v_lshl_or_b32 v48, v55, 16, v54
	s_waitcnt lgkmcnt(0)
	v_lshl_or_b32 v49, v57, 16, v56
	ds_write_b128 v151, v[42:45]
	ds_write_b128 v151, v[46:49] offset:16
	s_waitcnt lgkmcnt(0)
	s_barrier
; __global__ void __launch_bounds__(512, 2) fwd_mega(Args args) {
;     ...
;                   unsigned v[16];
; #pragma unroll
;                   for (int i = 0; i < 16; ++i) { const int key = (idx >> 10) ? (16 * kq + i) : (32 * (kq >> 1) + 16 * ((i >> 2) & 1) + 8 * (kq & 1) + 4 * (i >> 3) + (i & 3)); v[i] = T[key * QP + dd]; }
;                   u32x4 o0, o1; o0.x = v[0] | (v[1] << 16); o0.y = v[2] | (v[3] << 16); o0.z = v[4] | (v[5] << 16); o0.w = v[6] | (v[7] << 16);
;                   o1.x = v[8] | (v[9] << 16); o1.y = v[10] | (v[11] << 16); o1.z = v[12] | (v[13] << 16); o1.w = v[14] | (v[15] << 16);
;                   { const int rem = idx & 1023, b_ = rem >> 8, hq = (rem >> 5) & 7, st = rem & 31;
;                     bf16* dst = ((idx >> 10) ? VTG : VTA) + ((size_t)(b_ * 8 + hq) * 128 + dd) * SEQ + 64 * st + 16 * kq;
;                     *(u32x4*)dst = o0; *(u32x4*)(dst + 8) = o1; }
	ds_read_b128 v[42:45], v158
	ds_read_b128 v[46:49], v158 offset:9216
	s_mov_b64 s[36:37], 0x40000
	v_lshl_add_u64 v[52:53], v[50:51], 0, s[36:37]
	s_waitcnt lgkmcnt(1)
	global_store_dwordx4 v[50:51], v[42:45], off
	s_waitcnt lgkmcnt(0)
	global_store_dwordx4 v[52:53], v[46:49], off
	s_add_i32 s17, s23, s52
	s_cmpk_gt_i32 s17, 0x7ff
	s_cselect_b64 s[10:11], -1, 0
	s_waitcnt vmcnt(14)
	ds_write_b128 v14, v[68:71]
	ds_write_b128 v14, v[72:75] offset:128
	s_waitcnt lgkmcnt(0)
	s_barrier
	v_readlane_b32 s22, v254, 57
	s_add_i32 s22, s16, s22
	s_cmpk_lt_u32 s23, 0x400
	s_cselect_b64 vcc, -1, 0
	v_cndmask_b32_e32 v13, v10, v15, vcc
	v_mad_u64_u32 v[42:43], s[24:25], v13, s94, v[8:9]
	ds_read_u16 v13, v42
	ds_read_u16 v41, v42 offset:288
	ds_read_u16 v44, v42 offset:576
	ds_read_u16 v45, v42 offset:864
	v_cndmask_b32_e32 v42, v17, v18, vcc
	v_mad_u64_u32 v[42:43], s[24:25], v42, s94, v[8:9]
	ds_read_u16 v46, v42
	v_cndmask_b32_e32 v42, v19, v20, vcc
	v_mad_u64_u32 v[42:43], s[24:25], v42, s94, v[8:9]
	ds_read_u16 v47, v42
	v_cndmask_b32_e32 v42, v21, v22, vcc
	v_mad_u64_u32 v[42:43], s[24:25], v42, s94, v[8:9]
	ds_read_u16 v48, v42
	v_cndmask_b32_e32 v42, v23, v24, vcc
	v_mad_u64_u32 v[42:43], s[24:25], v42, s94, v[8:9]
	ds_read_u16 v49, v42
	v_cndmask_b32_e32 v42, v25, v26, vcc
	v_mad_u64_u32 v[42:43], s[24:25], v42, s94, v[8:9]
	ds_read_u16 v50, v42
	v_cndmask_b32_e32 v42, v27, v28, vcc
	v_mad_u64_u32 v[42:43], s[24:25], v42, s94, v[8:9]
	ds_read_u16 v51, v42
	v_cndmask_b32_e32 v42, v29, v30, vcc
	v_mad_u64_u32 v[42:43], s[24:25], v42, s94, v[8:9]
	ds_read_u16 v52, v42
	v_cndmask_b32_e32 v42, v31, v32, vcc
	v_mad_u64_u32 v[42:43], s[24:25], v42, s94, v[8:9]
	ds_read_u16 v53, v42
	v_cndmask_b32_e32 v42, v33, v34, vcc
	v_mad_u64_u32 v[42:43], s[24:25], v42, s94, v[8:9]
	ds_read_u16 v54, v42
	v_cndmask_b32_e32 v42, v35, v36, vcc
	v_mad_u64_u32 v[42:43], s[24:25], v42, s94, v[8:9]
	ds_read_u16 v55, v42
	v_cndmask_b32_e32 v42, v37, v38, vcc
	v_mad_u64_u32 v[42:43], s[24:25], v42, s94, v[8:9]
	ds_read_u16 v56, v42
	s_and_b64 s[24:25], vcc, exec
	v_cndmask_b32_e32 v42, v39, v40, vcc
	s_cselect_b32 s25, s29, s80
	s_cselect_b32 s24, s28, s71
	v_mad_u64_u32 v[42:43], s[36:37], v42, s94, v[8:9]
	s_and_b32 s23, s0, 0x7c0000
	ds_read_u16 v57, v42
	s_waitcnt lgkmcnt(14)
	v_lshl_or_b32 v42, v41, 16, v13
	v_or_b32_e32 v13, s23, v150
	v_lshlrev_b32_e32 v152, 1, v13
	s_and_b32 s16, s16, 0x7c0
	s_waitcnt lgkmcnt(12)
	v_lshl_or_b32 v43, v45, 16, v44
	s_waitcnt lgkmcnt(10)
	v_lshl_or_b32 v44, v47, 16, v46
	s_waitcnt lgkmcnt(6)
	v_lshl_or_b32 v46, v51, 16, v50
	v_lshl_add_u64 v[50:51], s[24:25], 0, v[152:153]
	s_lshl_b32 s26, s16, 1
	v_readlane_b32 s16, v254, 58
	v_lshl_add_u64 v[50:51], v[50:51], 0, s[26:27]
	s_add_i32 s14, s14, s16
	v_readlane_b32 s16, v254, 60
	v_lshl_or_b32 v45, v49, 16, v48
	v_lshl_add_u64 v[50:51], v[156:157], 1, v[50:51]
	s_add_i32 s15, s15, s33
	s_add_i32 s0, s0, s16
	s_and_b64 vcc, exec, s[10:11]
	s_mov_b32 s16, s22
	s_mov_b32 s23, s17
	s_waitcnt lgkmcnt(4)
	v_lshl_or_b32 v47, v53, 16, v52
	s_waitcnt lgkmcnt(2)
	v_lshl_or_b32 v48, v55, 16, v54
	s_waitcnt lgkmcnt(0)
	v_lshl_or_b32 v49, v57, 16, v56
	ds_write_b128 v151, v[42:45]
	ds_write_b128 v151, v[46:49] offset:16
	s_waitcnt lgkmcnt(0)
	s_barrier
	ds_read_b128 v[42:45], v158
	ds_read_b128 v[46:49], v158 offset:9216
	s_mov_b64 s[36:37], 0x40000
	v_lshl_add_u64 v[52:53], v[50:51], 0, s[36:37]
	s_waitcnt lgkmcnt(1)
	global_store_dwordx4 v[50:51], v[42:45], off
	s_waitcnt lgkmcnt(0)
	global_store_dwordx4 v[52:53], v[46:49], off
	s_add_i32 s17, s23, s52
	s_cmpk_gt_i32 s17, 0x7ff
	s_cselect_b64 s[10:11], -1, 0
	s_waitcnt vmcnt(14)
	ds_write_b128 v14, v[76:79]
	ds_write_b128 v14, v[80:83] offset:128
	s_waitcnt lgkmcnt(0)
	s_barrier
	v_readlane_b32 s22, v254, 57
	s_add_i32 s22, s16, s22
	s_cmpk_lt_u32 s23, 0x400
	s_cselect_b64 vcc, -1, 0
	v_cndmask_b32_e32 v13, v10, v15, vcc
	v_mad_u64_u32 v[42:43], s[24:25], v13, s94, v[8:9]
	ds_read_u16 v13, v42
	ds_read_u16 v41, v42 offset:288
	ds_read_u16 v44, v42 offset:576
	ds_read_u16 v45, v42 offset:864
	v_cndmask_b32_e32 v42, v17, v18, vcc
	v_mad_u64_u32 v[42:43], s[24:25], v42, s94, v[8:9]
	ds_read_u16 v46, v42
	v_cndmask_b32_e32 v42, v19, v20, vcc
	v_mad_u64_u32 v[42:43], s[24:25], v42, s94, v[8:9]
	ds_read_u16 v47, v42
	v_cndmask_b32_e32 v42, v21, v22, vcc
	v_mad_u64_u32 v[42:43], s[24:25], v42, s94, v[8:9]
	ds_read_u16 v48, v42
	v_cndmask_b32_e32 v42, v23, v24, vcc
	v_mad_u64_u32 v[42:43], s[24:25], v42, s94, v[8:9]
	ds_read_u16 v49, v42
	v_cndmask_b32_e32 v42, v25, v26, vcc
	v_mad_u64_u32 v[42:43], s[24:25], v42, s94, v[8:9]
	ds_read_u16 v50, v42
	v_cndmask_b32_e32 v42, v27, v28, vcc
	v_mad_u64_u32 v[42:43], s[24:25], v42, s94, v[8:9]
	ds_read_u16 v51, v42
	v_cndmask_b32_e32 v42, v29, v30, vcc
	v_mad_u64_u32 v[42:43], s[24:25], v42, s94, v[8:9]
	ds_read_u16 v52, v42
	v_cndmask_b32_e32 v42, v31, v32, vcc
	v_mad_u64_u32 v[42:43], s[24:25], v42, s94, v[8:9]
	ds_read_u16 v53, v42
	v_cndmask_b32_e32 v42, v33, v34, vcc
	v_mad_u64_u32 v[42:43], s[24:25], v42, s94, v[8:9]
	ds_read_u16 v54, v42
	v_cndmask_b32_e32 v42, v35, v36, vcc
	v_mad_u64_u32 v[42:43], s[24:25], v42, s94, v[8:9]
	ds_read_u16 v55, v42
	v_cndmask_b32_e32 v42, v37, v38, vcc
	v_mad_u64_u32 v[42:43], s[24:25], v42, s94, v[8:9]
	ds_read_u16 v56, v42
	s_and_b64 s[24:25], vcc, exec
	v_cndmask_b32_e32 v42, v39, v40, vcc
	s_cselect_b32 s25, s29, s80
	s_cselect_b32 s24, s28, s71
	v_mad_u64_u32 v[42:43], s[36:37], v42, s94, v[8:9]
	s_and_b32 s23, s0, 0x7c0000
	ds_read_u16 v57, v42
	s_waitcnt lgkmcnt(14)
	v_lshl_or_b32 v42, v41, 16, v13
	v_or_b32_e32 v13, s23, v150
	v_lshlrev_b32_e32 v152, 1, v13
	s_and_b32 s16, s16, 0x7c0
	s_waitcnt lgkmcnt(12)
	v_lshl_or_b32 v43, v45, 16, v44
	s_waitcnt lgkmcnt(10)
	v_lshl_or_b32 v44, v47, 16, v46
	s_waitcnt lgkmcnt(6)
	v_lshl_or_b32 v46, v51, 16, v50
	v_lshl_add_u64 v[50:51], s[24:25], 0, v[152:153]
	s_lshl_b32 s26, s16, 1
	v_readlane_b32 s16, v254, 58
	v_lshl_add_u64 v[50:51], v[50:51], 0, s[26:27]
	s_add_i32 s14, s14, s16
	v_readlane_b32 s16, v254, 60
	v_lshl_or_b32 v45, v49, 16, v48
	v_lshl_add_u64 v[50:51], v[156:157], 1, v[50:51]
	s_add_i32 s15, s15, s33
	s_add_i32 s0, s0, s16
	s_and_b64 vcc, exec, s[10:11]
	s_mov_b32 s16, s22
	s_mov_b32 s23, s17
	s_waitcnt lgkmcnt(4)
	v_lshl_or_b32 v47, v53, 16, v52
	s_waitcnt lgkmcnt(2)
	v_lshl_or_b32 v48, v55, 16, v54
	s_waitcnt lgkmcnt(0)
	v_lshl_or_b32 v49, v57, 16, v56
	ds_write_b128 v151, v[42:45]
	ds_write_b128 v151, v[46:49] offset:16
	s_waitcnt lgkmcnt(0)
	s_barrier
; #define LAS __attribute__((address_space(3)))
; __global__ void __launch_bounds__(512, 2) fwd_mega(Args args) {
;     ...
;               for (; idx < 2048; idx += G) {
;                   *(LAS u32x4*)(T + r * QP + 8 * j) = ta; *(LAS u32x4*)(T + r * QP + 64 + 8 * j) = tb;
;                   __syncthreads();
;                   if (idx + G < 2048) { const int i2 = idx + G, rem = i2 & 1023, b_ = rem >> 8, hq = (rem >> 5) & 7, st = rem & 31; const bf16* p = PROJ + (size_t)(b_ * SEQ + 64 * st + r) * PROJW + ((i2 >> 10) ? 4096 : 2048) + 128 * hq + 8 * j;
;                       ta = *(const u32x4*)p; tb = *(const u32x4*)(p + 64); }
;                   unsigned v[16];
; #pragma unroll
;                   for (int i = 0; i < 16; ++i) { const int key = (idx >> 10) ? (16 * kq + i) : (32 * (kq >> 1) + 16 * ((i >> 2) & 1) + 8 * (kq & 1) + 4 * (i >> 3) + (i & 3)); v[i] = T[key * QP + dd]; }
;                   u32x4 o0, o1; o0.x = v[0] | (v[1] << 16); o0.y = v[2] | (v[3] << 16); o0.z = v[4] | (v[5] << 16); o0.w = v[6] | (v[7] << 16);
;                   o1.x = v[8] | (v[9] << 16); o1.y = v[10] | (v[11] << 16); o1.z = v[12] | (v[13] << 16); o1.w = v[14] | (v[15] << 16);
;                   { const int rem = idx & 1023, b_ = rem >> 8, hq = (rem >> 5) & 7, st = rem & 31;
;                     bf16* dst = ((idx >> 10) ? VTG : VTA) + ((size_t)(b_ * 8 + hq) * 128 + dd) * SEQ + 64 * st + 16 * kq;
;                     *(u32x4*)dst = o0; *(u32x4*)(dst + 8) = o1; }
;                   __syncthreads();
	ds_read_b128 v[42:45], v158
	ds_read_b128 v[46:49], v158 offset:9216
	s_mov_b64 s[36:37], 0x40000
	v_lshl_add_u64 v[52:53], v[50:51], 0, s[36:37]
	s_waitcnt lgkmcnt(1)
	global_store_dwordx4 v[50:51], v[42:45], off
	s_waitcnt lgkmcnt(0)
	global_store_dwordx4 v[52:53], v[46:49], off
	s_add_i32 s17, s23, s52
	s_cmpk_gt_i32 s17, 0x7ff
	s_cselect_b64 s[10:11], -1, 0
	s_waitcnt vmcnt(14)
	ds_write_b128 v14, v[84:87]
	ds_write_b128 v14, v[88:91] offset:128
	s_waitcnt lgkmcnt(0)
	s_barrier
	v_readlane_b32 s22, v254, 57
	s_add_i32 s22, s16, s22
	s_cmpk_lt_u32 s23, 0x400
	s_cselect_b64 vcc, -1, 0
	v_cndmask_b32_e32 v13, v10, v15, vcc
	v_mad_u64_u32 v[42:43], s[24:25], v13, s94, v[8:9]
	ds_read_u16 v13, v42
	ds_read_u16 v41, v42 offset:288
	ds_read_u16 v44, v42 offset:576
	ds_read_u16 v45, v42 offset:864
	v_cndmask_b32_e32 v42, v17, v18, vcc
	v_mad_u64_u32 v[42:43], s[24:25], v42, s94, v[8:9]
	ds_read_u16 v46, v42
	v_cndmask_b32_e32 v42, v19, v20, vcc
	v_mad_u64_u32 v[42:43], s[24:25], v42, s94, v[8:9]
	ds_read_u16 v47, v42
	v_cndmask_b32_e32 v42, v21, v22, vcc
	v_mad_u64_u32 v[42:43], s[24:25], v42, s94, v[8:9]
	ds_read_u16 v48, v42
	v_cndmask_b32_e32 v42, v23, v24, vcc
	v_mad_u64_u32 v[42:43], s[24:25], v42, s94, v[8:9]
	ds_read_u16 v49, v42
	v_cndmask_b32_e32 v42, v25, v26, vcc
	v_mad_u64_u32 v[42:43], s[24:25], v42, s94, v[8:9]
	ds_read_u16 v50, v42
	v_cndmask_b32_e32 v42, v27, v28, vcc
	v_mad_u64_u32 v[42:43], s[24:25], v42, s94, v[8:9]
	ds_read_u16 v51, v42
	v_cndmask_b32_e32 v42, v29, v30, vcc
	v_mad_u64_u32 v[42:43], s[24:25], v42, s94, v[8:9]
	ds_read_u16 v52, v42
	v_cndmask_b32_e32 v42, v31, v32, vcc
	v_mad_u64_u32 v[42:43], s[24:25], v42, s94, v[8:9]
	ds_read_u16 v53, v42
	v_cndmask_b32_e32 v42, v33, v34, vcc
	v_mad_u64_u32 v[42:43], s[24:25], v42, s94, v[8:9]
	ds_read_u16 v54, v42
	v_cndmask_b32_e32 v42, v35, v36, vcc
	v_mad_u64_u32 v[42:43], s[24:25], v42, s94, v[8:9]
	ds_read_u16 v55, v42
	v_cndmask_b32_e32 v42, v37, v38, vcc
	v_mad_u64_u32 v[42:43], s[24:25], v42, s94, v[8:9]
	ds_read_u16 v56, v42
	s_and_b64 s[24:25], vcc, exec
	v_cndmask_b32_e32 v42, v39, v40, vcc
	s_cselect_b32 s25, s29, s80
	s_cselect_b32 s24, s28, s71
	v_mad_u64_u32 v[42:43], s[36:37], v42, s94, v[8:9]
	s_and_b32 s23, s0, 0x7c0000
	ds_read_u16 v57, v42
	s_waitcnt lgkmcnt(14)
	v_lshl_or_b32 v42, v41, 16, v13
	v_or_b32_e32 v13, s23, v150
	v_lshlrev_b32_e32 v152, 1, v13
	s_and_b32 s16, s16, 0x7c0
	s_waitcnt lgkmcnt(12)
	v_lshl_or_b32 v43, v45, 16, v44
	s_waitcnt lgkmcnt(10)
	v_lshl_or_b32 v44, v47, 16, v46
	s_waitcnt lgkmcnt(6)
	v_lshl_or_b32 v46, v51, 16, v50
	v_lshl_add_u64 v[50:51], s[24:25], 0, v[152:153]
	s_lshl_b32 s26, s16, 1
	v_readlane_b32 s16, v254, 58
	v_lshl_add_u64 v[50:51], v[50:51], 0, s[26:27]
	s_add_i32 s14, s14, s16
	v_readlane_b32 s16, v254, 60
	v_lshl_or_b32 v45, v49, 16, v48
	v_lshl_add_u64 v[50:51], v[156:157], 1, v[50:51]
	s_add_i32 s15, s15, s33
	s_add_i32 s0, s0, s16
	s_and_b64 vcc, exec, s[10:11]
	s_mov_b32 s16, s22
	s_mov_b32 s23, s17
	s_waitcnt lgkmcnt(4)
	v_lshl_or_b32 v47, v53, 16, v52
	s_waitcnt lgkmcnt(2)
	v_lshl_or_b32 v48, v55, 16, v54
	s_waitcnt lgkmcnt(0)
	v_lshl_or_b32 v49, v57, 16, v56
	ds_write_b128 v151, v[42:45]
	ds_write_b128 v151, v[46:49] offset:16
	s_waitcnt lgkmcnt(0)
	s_barrier
	ds_read_b128 v[42:45], v158
	ds_read_b128 v[46:49], v158 offset:9216
	s_mov_b64 s[36:37], 0x40000
	v_lshl_add_u64 v[52:53], v[50:51], 0, s[36:37]
	s_waitcnt lgkmcnt(1)
	global_store_dwordx4 v[50:51], v[42:45], off
	s_waitcnt lgkmcnt(0)
	global_store_dwordx4 v[52:53], v[46:49], off
	s_add_i32 s17, s23, s52
	s_cmpk_gt_i32 s17, 0x7ff
	s_cselect_b64 s[10:11], -1, 0
	s_waitcnt vmcnt(14)
	ds_write_b128 v14, v[92:95]
	ds_write_b128 v14, v[96:99] offset:128
	s_waitcnt lgkmcnt(0)
	s_barrier
	v_readlane_b32 s22, v254, 57
	s_add_i32 s22, s16, s22
	s_cmpk_lt_u32 s23, 0x400
	s_cselect_b64 vcc, -1, 0
	v_cndmask_b32_e32 v13, v10, v15, vcc
	v_mad_u64_u32 v[42:43], s[24:25], v13, s94, v[8:9]
	ds_read_u16 v13, v42
	ds_read_u16 v41, v42 offset:288
	ds_read_u16 v44, v42 offset:576
	ds_read_u16 v45, v42 offset:864
	v_cndmask_b32_e32 v42, v17, v18, vcc
	v_mad_u64_u32 v[42:43], s[24:25], v42, s94, v[8:9]
	ds_read_u16 v46, v42
	v_cndmask_b32_e32 v42, v19, v20, vcc
	v_mad_u64_u32 v[42:43], s[24:25], v42, s94, v[8:9]
	ds_read_u16 v47, v42
	v_cndmask_b32_e32 v42, v21, v22, vcc
	v_mad_u64_u32 v[42:43], s[24:25], v42, s94, v[8:9]
	ds_read_u16 v48, v42
	v_cndmask_b32_e32 v42, v23, v24, vcc
	v_mad_u64_u32 v[42:43], s[24:25], v42, s94, v[8:9]
	ds_read_u16 v49, v42
	v_cndmask_b32_e32 v42, v25, v26, vcc
	v_mad_u64_u32 v[42:43], s[24:25], v42, s94, v[8:9]
	ds_read_u16 v50, v42
	v_cndmask_b32_e32 v42, v27, v28, vcc
	v_mad_u64_u32 v[42:43], s[24:25], v42, s94, v[8:9]
	ds_read_u16 v51, v42
	v_cndmask_b32_e32 v42, v29, v30, vcc
	v_mad_u64_u32 v[42:43], s[24:25], v42, s94, v[8:9]
	ds_read_u16 v52, v42
	v_cndmask_b32_e32 v42, v31, v32, vcc
	v_mad_u64_u32 v[42:43], s[24:25], v42, s94, v[8:9]
	ds_read_u16 v53, v42
	v_cndmask_b32_e32 v42, v33, v34, vcc
	v_mad_u64_u32 v[42:43], s[24:25], v42, s94, v[8:9]
	ds_read_u16 v54, v42
	v_cndmask_b32_e32 v42, v35, v36, vcc
	v_mad_u64_u32 v[42:43], s[24:25], v42, s94, v[8:9]
	ds_read_u16 v55, v42
	v_cndmask_b32_e32 v42, v37, v38, vcc
	v_mad_u64_u32 v[42:43], s[24:25], v42, s94, v[8:9]
	ds_read_u16 v56, v42
	s_and_b64 s[24:25], vcc, exec
	v_cndmask_b32_e32 v42, v39, v40, vcc
	s_cselect_b32 s25, s29, s80
	s_cselect_b32 s24, s28, s71
	v_mad_u64_u32 v[42:43], s[36:37], v42, s94, v[8:9]
	s_and_b32 s23, s0, 0x7c0000
	ds_read_u16 v57, v42
	s_waitcnt lgkmcnt(14)
	v_lshl_or_b32 v42, v41, 16, v13
	v_or_b32_e32 v13, s23, v150
	v_lshlrev_b32_e32 v152, 1, v13
	s_and_b32 s16, s16, 0x7c0
	s_waitcnt lgkmcnt(12)
	v_lshl_or_b32 v43, v45, 16, v44
	s_waitcnt lgkmcnt(10)
	v_lshl_or_b32 v44, v47, 16, v46
	s_waitcnt lgkmcnt(6)
	v_lshl_or_b32 v46, v51, 16, v50
	v_lshl_add_u64 v[50:51], s[24:25], 0, v[152:153]
	s_lshl_b32 s26, s16, 1
	v_readlane_b32 s16, v254, 58
	v_lshl_add_u64 v[50:51], v[50:51], 0, s[26:27]
	s_add_i32 s14, s14, s16
	v_readlane_b32 s16, v254, 60
	v_lshl_or_b32 v45, v49, 16, v48
	v_lshl_add_u64 v[50:51], v[156:157], 1, v[50:51]
	s_add_i32 s15, s15, s33
	s_add_i32 s0, s0, s16
	s_and_b64 vcc, exec, s[10:11]
	s_mov_b32 s16, s22
	s_mov_b32 s23, s17
	s_waitcnt lgkmcnt(4)
	v_lshl_or_b32 v47, v53, 16, v52
	s_waitcnt lgkmcnt(2)
	v_lshl_or_b32 v48, v55, 16, v54
	s_waitcnt lgkmcnt(0)
	v_lshl_or_b32 v49, v57, 16, v56
	ds_write_b128 v151, v[42:45]
	ds_write_b128 v151, v[46:49] offset:16
	s_waitcnt lgkmcnt(0)
	s_barrier
; #define LAS __attribute__((address_space(3)))
; __global__ void __launch_bounds__(512, 2) fwd_mega(Args args) {
;     ...
;               for (; idx < 2048; idx += G) {
;                   *(LAS u32x4*)(T + r * QP + 8 * j) = ta; *(LAS u32x4*)(T + r * QP + 64 + 8 * j) = tb;
;                   __syncthreads();
;                   if (idx + G < 2048) { const int i2 = idx + G, rem = i2 & 1023, b_ = rem >> 8, hq = (rem >> 5) & 7, st = rem & 31; const bf16* p = PROJ + (size_t)(b_ * SEQ + 64 * st + r) * PROJW + ((i2 >> 10) ? 4096 : 2048) + 128 * hq + 8 * j;
;                       ta = *(const u32x4*)p; tb = *(const u32x4*)(p + 64); }
;                   unsigned v[16];
; #pragma unroll
;                   for (int i = 0; i < 16; ++i) { const int key = (idx >> 10) ? (16 * kq + i) : (32 * (kq >> 1) + 16 * ((i >> 2) & 1) + 8 * (kq & 1) + 4 * (i >> 3) + (i & 3)); v[i] = T[key * QP + dd]; }
;                   u32x4 o0, o1; o0.x = v[0] | (v[1] << 16); o0.y = v[2] | (v[3] << 16); o0.z = v[4] | (v[5] << 16); o0.w = v[6] | (v[7] << 16);
;                   o1.x = v[8] | (v[9] << 16); o1.y = v[10] | (v[11] << 16); o1.z = v[12] | (v[13] << 16); o1.w = v[14] | (v[15] << 16);
;                   { const int rem = idx & 1023, b_ = rem >> 8, hq = (rem >> 5) & 7, st = rem & 31;
;                     bf16* dst = ((idx >> 10) ? VTG : VTA) + ((size_t)(b_ * 8 + hq) * 128 + dd) * SEQ + 64 * st + 16 * kq;
;                     *(u32x4*)dst = o0; *(u32x4*)(dst + 8) = o1; }
;                   __syncthreads();
	ds_read_b128 v[42:45], v158
	ds_read_b128 v[46:49], v158 offset:9216
	s_mov_b64 s[36:37], 0x40000
	v_lshl_add_u64 v[52:53], v[50:51], 0, s[36:37]
	s_waitcnt lgkmcnt(1)
	global_store_dwordx4 v[50:51], v[42:45], off
	s_waitcnt lgkmcnt(0)
	global_store_dwordx4 v[52:53], v[46:49], off
	s_add_i32 s17, s23, s52
	s_cmpk_gt_i32 s17, 0x7ff
	s_cselect_b64 s[10:11], -1, 0
	s_waitcnt vmcnt(14)
	ds_write_b128 v14, v[108:111]
	ds_write_b128 v14, v[112:115] offset:128
	s_waitcnt lgkmcnt(0)
	s_barrier
	v_readlane_b32 s22, v254, 57
	s_add_i32 s22, s16, s22
	s_cmpk_lt_u32 s23, 0x400
	s_cselect_b64 vcc, -1, 0
	v_cndmask_b32_e32 v13, v10, v15, vcc
	v_mad_u64_u32 v[42:43], s[24:25], v13, s94, v[8:9]
	ds_read_u16 v13, v42
	ds_read_u16 v41, v42 offset:288
	ds_read_u16 v44, v42 offset:576
	ds_read_u16 v45, v42 offset:864
	v_cndmask_b32_e32 v42, v17, v18, vcc
	v_mad_u64_u32 v[42:43], s[24:25], v42, s94, v[8:9]
	ds_read_u16 v46, v42
	v_cndmask_b32_e32 v42, v19, v20, vcc
	v_mad_u64_u32 v[42:43], s[24:25], v42, s94, v[8:9]
	ds_read_u16 v47, v42
	v_cndmask_b32_e32 v42, v21, v22, vcc
	v_mad_u64_u32 v[42:43], s[24:25], v42, s94, v[8:9]
	ds_read_u16 v48, v42
	v_cndmask_b32_e32 v42, v23, v24, vcc
	v_mad_u64_u32 v[42:43], s[24:25], v42, s94, v[8:9]
	ds_read_u16 v49, v42
	v_cndmask_b32_e32 v42, v25, v26, vcc
	v_mad_u64_u32 v[42:43], s[24:25], v42, s94, v[8:9]
	ds_read_u16 v50, v42
	v_cndmask_b32_e32 v42, v27, v28, vcc
	v_mad_u64_u32 v[42:43], s[24:25], v42, s94, v[8:9]
	ds_read_u16 v51, v42
	v_cndmask_b32_e32 v42, v29, v30, vcc
	v_mad_u64_u32 v[42:43], s[24:25], v42, s94, v[8:9]
	ds_read_u16 v52, v42
	v_cndmask_b32_e32 v42, v31, v32, vcc
	v_mad_u64_u32 v[42:43], s[24:25], v42, s94, v[8:9]
	ds_read_u16 v53, v42
	v_cndmask_b32_e32 v42, v33, v34, vcc
	v_mad_u64_u32 v[42:43], s[24:25], v42, s94, v[8:9]
	ds_read_u16 v54, v42
	v_cndmask_b32_e32 v42, v35, v36, vcc
	v_mad_u64_u32 v[42:43], s[24:25], v42, s94, v[8:9]
	ds_read_u16 v55, v42
	v_cndmask_b32_e32 v42, v37, v38, vcc
	v_mad_u64_u32 v[42:43], s[24:25], v42, s94, v[8:9]
	ds_read_u16 v56, v42
	s_and_b64 s[24:25], vcc, exec
	v_cndmask_b32_e32 v42, v39, v40, vcc
	s_cselect_b32 s25, s29, s80
	s_cselect_b32 s24, s28, s71
	v_mad_u64_u32 v[42:43], s[36:37], v42, s94, v[8:9]
	s_and_b32 s23, s0, 0x7c0000
	ds_read_u16 v57, v42
	s_waitcnt lgkmcnt(14)
	v_lshl_or_b32 v42, v41, 16, v13
	v_or_b32_e32 v13, s23, v150
	v_lshlrev_b32_e32 v152, 1, v13
	s_and_b32 s16, s16, 0x7c0
	s_waitcnt lgkmcnt(12)
	v_lshl_or_b32 v43, v45, 16, v44
	s_waitcnt lgkmcnt(10)
	v_lshl_or_b32 v44, v47, 16, v46
	s_waitcnt lgkmcnt(6)
	v_lshl_or_b32 v46, v51, 16, v50
	v_lshl_add_u64 v[50:51], s[24:25], 0, v[152:153]
	s_lshl_b32 s26, s16, 1
	v_readlane_b32 s16, v254, 58
	v_lshl_add_u64 v[50:51], v[50:51], 0, s[26:27]
	s_add_i32 s14, s14, s16
	v_readlane_b32 s16, v254, 60
	v_lshl_or_b32 v45, v49, 16, v48
	v_lshl_add_u64 v[50:51], v[156:157], 1, v[50:51]
	s_add_i32 s15, s15, s33
	s_add_i32 s0, s0, s16
	s_and_b64 vcc, exec, s[10:11]
	s_mov_b32 s16, s22
	s_mov_b32 s23, s17
	s_waitcnt lgkmcnt(4)
	v_lshl_or_b32 v47, v53, 16, v52
	s_waitcnt lgkmcnt(2)
	v_lshl_or_b32 v48, v55, 16, v54
	s_waitcnt lgkmcnt(0)
	v_lshl_or_b32 v49, v57, 16, v56
	ds_write_b128 v151, v[42:45]
	ds_write_b128 v151, v[46:49] offset:16
	s_waitcnt lgkmcnt(0)
	s_barrier
	ds_read_b128 v[42:45], v158
	ds_read_b128 v[46:49], v158 offset:9216
	s_mov_b64 s[36:37], 0x40000
	v_lshl_add_u64 v[52:53], v[50:51], 0, s[36:37]
	s_waitcnt lgkmcnt(1)
	global_store_dwordx4 v[50:51], v[42:45], off
	s_waitcnt lgkmcnt(0)
	global_store_dwordx4 v[52:53], v[46:49], off
	s_add_i32 s17, s23, s52
	s_cmpk_gt_i32 s17, 0x7ff
	s_cselect_b64 s[10:11], -1, 0
	s_waitcnt vmcnt(14)
	ds_write_b128 v14, v[116:119]
	ds_write_b128 v14, v[120:123] offset:128
	s_waitcnt lgkmcnt(0)
	s_barrier
; #define LAS __attribute__((address_space(3)))
; __global__ void __launch_bounds__(512, 2) fwd_mega(Args args) {
;     ...
;               for (; idx < 2048; idx += G) {
;                   *(LAS u32x4*)(T + r * QP + 8 * j) = ta; *(LAS u32x4*)(T + r * QP + 64 + 8 * j) = tb;
;                   __syncthreads();
;                   if (idx + G < 2048) { const int i2 = idx + G, rem = i2 & 1023, b_ = rem >> 8, hq = (rem >> 5) & 7, st = rem & 31; const bf16* p = PROJ + (size_t)(b_ * SEQ + 64 * st + r) * PROJW + ((i2 >> 10) ? 4096 : 2048) + 128 * hq + 8 * j;
;                       ta = *(const u32x4*)p; tb = *(const u32x4*)(p + 64); }
;                   unsigned v[16];
; #pragma unroll
;                   for (int i = 0; i < 16; ++i) { const int key = (idx >> 10) ? (16 * kq + i) : (32 * (kq >> 1) + 16 * ((i >> 2) & 1) + 8 * (kq & 1) + 4 * (i >> 3) + (i & 3)); v[i] = T[key * QP + dd]; }
;                   u32x4 o0, o1; o0.x = v[0] | (v[1] << 16); o0.y = v[2] | (v[3] << 16); o0.z = v[4] | (v[5] << 16); o0.w = v[6] | (v[7] << 16);
;                   o1.x = v[8] | (v[9] << 16); o1.y = v[10] | (v[11] << 16); o1.z = v[12] | (v[13] << 16); o1.w = v[14] | (v[15] << 16);
;                   { const int rem = idx & 1023, b_ = rem >> 8, hq = (rem >> 5) & 7, st = rem & 31;
;                     bf16* dst = ((idx >> 10) ? VTG : VTA) + ((size_t)(b_ * 8 + hq) * 128 + dd) * SEQ + 64 * st + 16 * kq;
;                     *(u32x4*)dst = o0; *(u32x4*)(dst + 8) = o1; }
;                   __syncthreads();
	v_readlane_b32 s22, v254, 57
	s_add_i32 s22, s16, s22
	s_cmpk_lt_u32 s23, 0x400
	s_cselect_b64 vcc, -1, 0
	v_cndmask_b32_e32 v13, v10, v15, vcc
	v_mad_u64_u32 v[42:43], s[24:25], v13, s94, v[8:9]
	ds_read_u16 v13, v42
	ds_read_u16 v41, v42 offset:288
	ds_read_u16 v44, v42 offset:576
	ds_read_u16 v45, v42 offset:864
	v_cndmask_b32_e32 v42, v17, v18, vcc
	v_mad_u64_u32 v[42:43], s[24:25], v42, s94, v[8:9]
	ds_read_u16 v46, v42
	v_cndmask_b32_e32 v42, v19, v20, vcc
	v_mad_u64_u32 v[42:43], s[24:25], v42, s94, v[8:9]
	ds_read_u16 v47, v42
	v_cndmask_b32_e32 v42, v21, v22, vcc
	v_mad_u64_u32 v[42:43], s[24:25], v42, s94, v[8:9]
	ds_read_u16 v48, v42
	v_cndmask_b32_e32 v42, v23, v24, vcc
	v_mad_u64_u32 v[42:43], s[24:25], v42, s94, v[8:9]
	ds_read_u16 v49, v42
	v_cndmask_b32_e32 v42, v25, v26, vcc
	v_mad_u64_u32 v[42:43], s[24:25], v42, s94, v[8:9]
	ds_read_u16 v50, v42
	v_cndmask_b32_e32 v42, v27, v28, vcc
	v_mad_u64_u32 v[42:43], s[24:25], v42, s94, v[8:9]
	ds_read_u16 v51, v42
	v_cndmask_b32_e32 v42, v29, v30, vcc
	v_mad_u64_u32 v[42:43], s[24:25], v42, s94, v[8:9]
	ds_read_u16 v52, v42
	v_cndmask_b32_e32 v42, v31, v32, vcc
	v_mad_u64_u32 v[42:43], s[24:25], v42, s94, v[8:9]
	ds_read_u16 v53, v42
	v_cndmask_b32_e32 v42, v33, v34, vcc
	v_mad_u64_u32 v[42:43], s[24:25], v42, s94, v[8:9]
	ds_read_u16 v54, v42
	v_cndmask_b32_e32 v42, v35, v36, vcc
	v_mad_u64_u32 v[42:43], s[24:25], v42, s94, v[8:9]
	ds_read_u16 v55, v42
	v_cndmask_b32_e32 v42, v37, v38, vcc
	v_mad_u64_u32 v[42:43], s[24:25], v42, s94, v[8:9]
	ds_read_u16 v56, v42
	s_and_b64 s[24:25], vcc, exec
	v_cndmask_b32_e32 v42, v39, v40, vcc
	s_cselect_b32 s25, s29, s80
	s_cselect_b32 s24, s28, s71
	v_mad_u64_u32 v[42:43], s[36:37], v42, s94, v[8:9]
	s_and_b32 s23, s0, 0x7c0000
	ds_read_u16 v57, v42
	s_waitcnt lgkmcnt(14)
	v_lshl_or_b32 v42, v41, 16, v13
	v_or_b32_e32 v13, s23, v150
	v_lshlrev_b32_e32 v152, 1, v13
	s_and_b32 s16, s16, 0x7c0
	s_waitcnt lgkmcnt(12)
	v_lshl_or_b32 v43, v45, 16, v44
	s_waitcnt lgkmcnt(10)
	v_lshl_or_b32 v44, v47, 16, v46
	s_waitcnt lgkmcnt(6)
	v_lshl_or_b32 v46, v51, 16, v50
	v_lshl_add_u64 v[50:51], s[24:25], 0, v[152:153]
	s_lshl_b32 s26, s16, 1
	v_readlane_b32 s16, v254, 58
	v_lshl_add_u64 v[50:51], v[50:51], 0, s[26:27]
	s_add_i32 s14, s14, s16
	v_readlane_b32 s16, v254, 60
	v_lshl_or_b32 v45, v49, 16, v48
	v_lshl_add_u64 v[50:51], v[156:157], 1, v[50:51]
	s_add_i32 s15, s15, s33
	s_add_i32 s0, s0, s16
	s_and_b64 vcc, exec, s[10:11]
	s_mov_b32 s16, s22
	s_mov_b32 s23, s17
	s_waitcnt lgkmcnt(4)
	v_lshl_or_b32 v47, v53, 16, v52
	s_waitcnt lgkmcnt(2)
	v_lshl_or_b32 v48, v55, 16, v54
	s_waitcnt lgkmcnt(0)
	v_lshl_or_b32 v49, v57, 16, v56
	ds_write_b128 v151, v[42:45]
	ds_write_b128 v151, v[46:49] offset:16
	s_waitcnt lgkmcnt(0)
	s_barrier
	ds_read_b128 v[42:45], v158
	ds_read_b128 v[46:49], v158 offset:9216
	s_mov_b64 s[36:37], 0x40000
	v_lshl_add_u64 v[52:53], v[50:51], 0, s[36:37]
	s_waitcnt lgkmcnt(1)
	global_store_dwordx4 v[50:51], v[42:45], off
	s_waitcnt lgkmcnt(0)
	global_store_dwordx4 v[52:53], v[46:49], off
	s_add_i32 s17, s23, s52
	s_cmpk_gt_i32 s17, 0x7ff
	s_cselect_b64 s[10:11], -1, 0
	s_waitcnt vmcnt(14)
	ds_write_b128 v14, v[126:129]
	ds_write_b128 v14, v[130:133] offset:128
	s_waitcnt lgkmcnt(0)
	s_barrier
	v_readlane_b32 s22, v254, 57
	s_add_i32 s22, s16, s22
	s_cmpk_lt_u32 s23, 0x400
	s_cselect_b64 vcc, -1, 0
	v_cndmask_b32_e32 v13, v10, v15, vcc
	v_mad_u64_u32 v[42:43], s[24:25], v13, s94, v[8:9]
	ds_read_u16 v13, v42
	ds_read_u16 v41, v42 offset:288
	ds_read_u16 v44, v42 offset:576
	ds_read_u16 v45, v42 offset:864
	v_cndmask_b32_e32 v42, v17, v18, vcc
	v_mad_u64_u32 v[42:43], s[24:25], v42, s94, v[8:9]
	ds_read_u16 v46, v42
	v_cndmask_b32_e32 v42, v19, v20, vcc
	v_mad_u64_u32 v[42:43], s[24:25], v42, s94, v[8:9]
	ds_read_u16 v47, v42
	v_cndmask_b32_e32 v42, v21, v22, vcc
	v_mad_u64_u32 v[42:43], s[24:25], v42, s94, v[8:9]
	ds_read_u16 v48, v42
	v_cndmask_b32_e32 v42, v23, v24, vcc
	v_mad_u64_u32 v[42:43], s[24:25], v42, s94, v[8:9]
	ds_read_u16 v49, v42
	v_cndmask_b32_e32 v42, v25, v26, vcc
	v_mad_u64_u32 v[42:43], s[24:25], v42, s94, v[8:9]
	ds_read_u16 v50, v42
	v_cndmask_b32_e32 v42, v27, v28, vcc
	v_mad_u64_u32 v[42:43], s[24:25], v42, s94, v[8:9]
	ds_read_u16 v51, v42
	v_cndmask_b32_e32 v42, v29, v30, vcc
	v_mad_u64_u32 v[42:43], s[24:25], v42, s94, v[8:9]
	ds_read_u16 v52, v42
	v_cndmask_b32_e32 v42, v31, v32, vcc
	v_mad_u64_u32 v[42:43], s[24:25], v42, s94, v[8:9]
	ds_read_u16 v53, v42
	v_cndmask_b32_e32 v42, v33, v34, vcc
	v_mad_u64_u32 v[42:43], s[24:25], v42, s94, v[8:9]
	ds_read_u16 v54, v42
	v_cndmask_b32_e32 v42, v35, v36, vcc
	v_mad_u64_u32 v[42:43], s[24:25], v42, s94, v[8:9]
	ds_read_u16 v55, v42
	v_cndmask_b32_e32 v42, v37, v38, vcc
	v_mad_u64_u32 v[42:43], s[24:25], v42, s94, v[8:9]
	ds_read_u16 v56, v42
	s_and_b64 s[24:25], vcc, exec
	v_cndmask_b32_e32 v42, v39, v40, vcc
	s_cselect_b32 s25, s29, s80
	s_cselect_b32 s24, s28, s71
	v_mad_u64_u32 v[42:43], s[36:37], v42, s94, v[8:9]
	s_and_b32 s23, s0, 0x7c0000
	ds_read_u16 v57, v42
	s_waitcnt lgkmcnt(14)
	v_lshl_or_b32 v42, v41, 16, v13
	v_or_b32_e32 v13, s23, v150
	v_lshlrev_b32_e32 v152, 1, v13
	s_and_b32 s16, s16, 0x7c0
	s_waitcnt lgkmcnt(12)
	v_lshl_or_b32 v43, v45, 16, v44
	s_waitcnt lgkmcnt(10)
	v_lshl_or_b32 v44, v47, 16, v46
	s_waitcnt lgkmcnt(6)
	v_lshl_or_b32 v46, v51, 16, v50
	v_lshl_add_u64 v[50:51], s[24:25], 0, v[152:153]
	s_lshl_b32 s26, s16, 1
	v_readlane_b32 s16, v254, 58
	v_lshl_add_u64 v[50:51], v[50:51], 0, s[26:27]
	s_add_i32 s14, s14, s16
	v_readlane_b32 s16, v254, 60
	v_lshl_or_b32 v45, v49, 16, v48
	v_lshl_add_u64 v[50:51], v[156:157], 1, v[50:51]
	s_add_i32 s15, s15, s33
	s_add_i32 s0, s0, s16
	s_and_b64 vcc, exec, s[10:11]
	s_mov_b32 s16, s22
	s_mov_b32 s23, s17
	s_waitcnt lgkmcnt(4)
	v_lshl_or_b32 v47, v53, 16, v52
	s_waitcnt lgkmcnt(2)
	v_lshl_or_b32 v48, v55, 16, v54
	s_waitcnt lgkmcnt(0)
	v_lshl_or_b32 v49, v57, 16, v56
	ds_write_b128 v151, v[42:45]
	ds_write_b128 v151, v[46:49] offset:16
	s_waitcnt lgkmcnt(0)
	s_barrier
	ds_read_b128 v[42:45], v158
	ds_read_b128 v[46:49], v158 offset:9216
	s_mov_b64 s[36:37], 0x40000
	v_lshl_add_u64 v[52:53], v[50:51], 0, s[36:37]
	s_waitcnt lgkmcnt(1)
	global_store_dwordx4 v[50:51], v[42:45], off
	s_waitcnt lgkmcnt(0)
	global_store_dwordx4 v[52:53], v[46:49], off
	s_barrier
	s_branch .LBB0_153
